# PEER stage B: per-expert scalars prefetched with the row gather, counted vmcnt(20) double buffering, one workgroup barrier per iteration to keep waves on the same L2-resident table slice
# speedup vs baseline: 1.0296x; 1.0143x over previous
.LBB0_787:
	s_waitcnt vmcnt(0) lgkmcnt(0)
	s_and_b64 vcc, exec, s[56:57]
	s_cbranch_vccz .LBB0_804
	ds_read_b128 v[0:3], v177 offset:2576
	ds_read_b128 v[12:15], v177 offset:2560
	v_add_u32_e32 v250, v183, v177
	ds_read_u16 v250, v250 offset:2560
	v_mov_b32_e32 v5, v137
	v_ashrrev_i32_e32 v173, 31, v172
	s_waitcnt vmcnt(0)
	v_cvt_f32_u32_e32 v68, s81
	s_waitcnt lgkmcnt(1)
	v_lshlrev_b32_sdwa v4, v188, v3 dst_sel:DWORD dst_unused:UNUSED_PAD src0_sel:DWORD src1_sel:WORD_0
	v_lshlrev_b32_sdwa v136, v188, v3 dst_sel:DWORD dst_unused:UNUSED_PAD src0_sel:DWORD src1_sel:WORD_1
	v_lshl_add_u64 v[6:7], v[152:153], 0, v[136:137]
	v_lshl_add_u64 v[4:5], v[152:153], 0, v[4:5]
	v_lshlrev_b32_sdwa v136, v188, v2 dst_sel:DWORD dst_unused:UNUSED_PAD src0_sel:DWORD src1_sel:WORD_1
	global_load_dwordx4 v[64:67], v[6:7], off
	global_load_dwordx4 v[60:63], v[4:5], off
	v_lshlrev_b32_sdwa v4, v188, v2 dst_sel:DWORD dst_unused:UNUSED_PAD src0_sel:DWORD src1_sel:WORD_0
	v_lshl_add_u64 v[2:3], v[152:153], 0, v[136:137]
	v_mov_b32_e32 v5, v137
	v_lshl_add_u64 v[4:5], v[152:153], 0, v[4:5]
	global_load_dwordx4 v[56:59], v[2:3], off
	global_load_dwordx4 v[52:55], v[4:5], off
	v_lshlrev_b32_sdwa v2, v188, v1 dst_sel:DWORD dst_unused:UNUSED_PAD src0_sel:DWORD src1_sel:WORD_0
	v_lshlrev_b32_sdwa v136, v188, v1 dst_sel:DWORD dst_unused:UNUSED_PAD src0_sel:DWORD src1_sel:WORD_1
	v_mov_b32_e32 v3, v137
	v_lshl_add_u64 v[4:5], v[152:153], 0, v[136:137]
	v_lshl_add_u64 v[2:3], v[152:153], 0, v[2:3]
	v_lshlrev_b32_sdwa v136, v188, v0 dst_sel:DWORD dst_unused:UNUSED_PAD src0_sel:DWORD src1_sel:WORD_1
	global_load_dwordx4 v[48:51], v[4:5], off
	global_load_dwordx4 v[44:47], v[2:3], off
	v_lshlrev_b32_sdwa v2, v188, v0 dst_sel:DWORD dst_unused:UNUSED_PAD src0_sel:DWORD src1_sel:WORD_0
	v_lshl_add_u64 v[0:1], v[152:153], 0, v[136:137]
	v_mov_b32_e32 v3, v137
	v_lshl_add_u64 v[2:3], v[152:153], 0, v[2:3]
	global_load_dwordx4 v[40:43], v[0:1], off
	global_load_dwordx4 v[36:39], v[2:3], off
	s_waitcnt lgkmcnt(0)
	v_lshlrev_b32_sdwa v0, v188, v15 dst_sel:DWORD dst_unused:UNUSED_PAD src0_sel:DWORD src1_sel:WORD_0
	v_lshlrev_b32_sdwa v136, v188, v15 dst_sel:DWORD dst_unused:UNUSED_PAD src0_sel:DWORD src1_sel:WORD_1
	v_mov_b32_e32 v1, v137
	v_lshl_add_u64 v[2:3], v[152:153], 0, v[136:137]
	v_lshl_add_u64 v[0:1], v[152:153], 0, v[0:1]
	global_load_dwordx4 v[32:35], v[2:3], off
	global_load_dwordx4 v[28:31], v[0:1], off
	v_lshlrev_b32_sdwa v0, v188, v14 dst_sel:DWORD dst_unused:UNUSED_PAD src0_sel:DWORD src1_sel:WORD_0
	v_lshlrev_b32_sdwa v136, v188, v14 dst_sel:DWORD dst_unused:UNUSED_PAD src0_sel:DWORD src1_sel:WORD_1
	v_mov_b32_e32 v1, v137
	v_lshl_add_u64 v[2:3], v[152:153], 0, v[136:137]
	v_lshl_add_u64 v[0:1], v[152:153], 0, v[0:1]
	global_load_dwordx4 v[24:27], v[2:3], off
	global_load_dwordx4 v[20:23], v[0:1], off
	v_lshlrev_b32_sdwa v0, v188, v13 dst_sel:DWORD dst_unused:UNUSED_PAD src0_sel:DWORD src1_sel:WORD_0
	v_lshlrev_b32_sdwa v136, v188, v13 dst_sel:DWORD dst_unused:UNUSED_PAD src0_sel:DWORD src1_sel:WORD_1
	v_mov_b32_e32 v1, v137
	v_lshl_add_u64 v[2:3], v[152:153], 0, v[136:137]
	v_lshl_add_u64 v[0:1], v[152:153], 0, v[0:1]
	global_load_dwordx4 v[4:7], v[2:3], off
	global_load_dwordx4 v[8:11], v[0:1], off
	v_lshlrev_b32_sdwa v0, v188, v12 dst_sel:DWORD dst_unused:UNUSED_PAD src0_sel:DWORD src1_sel:WORD_0
	v_lshlrev_b32_sdwa v136, v188, v12 dst_sel:DWORD dst_unused:UNUSED_PAD src0_sel:DWORD src1_sel:WORD_1
	v_mov_b32_e32 v1, v137
	v_lshl_add_u64 v[2:3], v[152:153], 0, v[136:137]
	v_lshl_add_u64 v[0:1], v[152:153], 0, v[0:1]
	global_load_dwordx4 v[12:15], v[2:3], off
	global_load_dwordx4 v[16:19], v[0:1], off
	v_lshlrev_b64 v[0:1], 10, v[172:173]
	v_lshl_add_u64 v[0:1], v[138:139], 0, v[0:1]
	global_load_dwordx4 v[0:3], v[0:1], off
	v_lshlrev_b32_e32 v250, 2, v250
	global_load_dword v244, v250, s[40:41]
	global_load_dword v245, v250, s[36:37]
	global_load_dword v246, v250, s[38:39]
	v_rcp_iflag_f32_e32 v68, v68
	s_sub_i32 s20, 0, s81
	s_lshl_b32 s8, s81, 8
	s_sub_i32 s21, 32, s8
	v_mul_f32_e32 v68, 0x4f7ffffe, v68
	v_cvt_u32_f32_e32 v68, v68
	s_lshl_b32 s8, s81, 7
	s_lshl_b32 s18, s81, 3
	s_sub_i32 s8, 16, s8
	v_readfirstlane_b32 s6, v68
	s_mul_i32 s7, s20, s6
	s_mul_hi_u32 s7, s6, s7
	s_add_i32 s26, s6, s7
	s_lshl_b64 s[6:7], s[26:27], 1
	s_mov_b32 s19, 0
	s_lshl_b32 s24, s8, 2
	s_lshl_b32 s25, s8, 1
	s_sub_i32 s82, 0, s18
	s_mov_b64 s[8:9], 0
	s_mov_b64 s[10:11], s[26:27]
	v_mov_b32_e32 v157, v183
	v_mov_b32_e32 v159, v182
	s_mov_b32 s26, 0
	s_mov_b64 s[12:13], s[6:7]
	s_mov_b32 s16, 0
	s_branch .LBB0_790

.LBB0_790:
	s_barrier
	s_not_b32 s17, s11
	s_mul_i32 s15, s81, s11
	s_mul_i32 s17, s81, s17
	s_add_i32 s17, s17, s16
	s_sub_i32 s15, s16, s15
	s_not_b32 s14, s9
	s_add_i32 s15, s15, 1
	s_add_i32 s83, s11, 1
	s_add_i32 s17, s17, 1
	s_cmp_ge_u32 s15, s81
	s_cselect_b32 s83, s83, s11
	s_cselect_b32 s15, s17, s15
	s_add_i32 s17, s83, 1
	s_cmp_ge_u32 s15, s81
	s_cselect_b32 s83, s17, s83
	s_mul_i32 s15, s20, s83
	s_add_i32 s15, s16, s15
	s_add_i32 s15, s15, 1
	s_mul_i32 s15, s15, s33
	v_add_u32_e32 v68, s15, v172
	s_mul_i32 s15, s25, s83
	v_add_u32_e32 v161, s15, v176
	v_add_u32_e32 v76, s26, v161
	v_add_u32_e32 v250, v183, v76
	ds_read_b128 v[72:75], v76 offset:2816
	ds_read_b128 v[78:81], v76 offset:2832
	ds_read_u16 v250, v250 offset:2816
	v_ashrrev_i32_e32 v69, 31, v68
	v_lshlrev_b64 v[68:69], 10, v[68:69]
	v_mov_b32_e32 v77, v137
	s_waitcnt lgkmcnt(1)
	v_lshlrev_b32_sdwa v76, v188, v72 dst_sel:DWORD dst_unused:UNUSED_PAD src0_sel:DWORD src1_sel:WORD_1
	v_lshlrev_b32_sdwa v136, v188, v72 dst_sel:DWORD dst_unused:UNUSED_PAD src0_sel:DWORD src1_sel:WORD_0
	v_lshl_add_u64 v[68:69], v[138:139], 0, v[68:69]
	v_lshl_add_u64 v[82:83], v[152:153], 0, v[136:137]
	v_lshl_add_u64 v[76:77], v[152:153], 0, v[76:77]
	v_lshlrev_b32_sdwa v72, v188, v73 dst_sel:DWORD dst_unused:UNUSED_PAD src0_sel:DWORD src1_sel:WORD_1
	v_lshlrev_b32_sdwa v136, v188, v73 dst_sel:DWORD dst_unused:UNUSED_PAD src0_sel:DWORD src1_sel:WORD_0
	v_mov_b32_e32 v73, v137
	global_load_dwordx4 v[68:71], v[68:69], off
	s_nop 0
	global_load_dwordx4 v[132:135], v[82:83], off
	global_load_dwordx4 v[124:127], v[76:77], off
	v_lshl_add_u64 v[76:77], v[152:153], 0, v[136:137]
	v_lshl_add_u64 v[72:73], v[152:153], 0, v[72:73]
	global_load_dwordx4 v[128:131], v[76:77], off
	global_load_dwordx4 v[116:119], v[72:73], off
	v_lshlrev_b32_sdwa v72, v188, v74 dst_sel:DWORD dst_unused:UNUSED_PAD src0_sel:DWORD src1_sel:WORD_1
	v_lshlrev_b32_sdwa v136, v188, v74 dst_sel:DWORD dst_unused:UNUSED_PAD src0_sel:DWORD src1_sel:WORD_0
	v_mov_b32_e32 v73, v137
	v_lshl_add_u64 v[76:77], v[152:153], 0, v[136:137]
	v_lshl_add_u64 v[72:73], v[152:153], 0, v[72:73]
	global_load_dwordx4 v[120:123], v[76:77], off
	global_load_dwordx4 v[108:111], v[72:73], off
	v_lshlrev_b32_sdwa v72, v188, v75 dst_sel:DWORD dst_unused:UNUSED_PAD src0_sel:DWORD src1_sel:WORD_1
	v_lshlrev_b32_sdwa v136, v188, v75 dst_sel:DWORD dst_unused:UNUSED_PAD src0_sel:DWORD src1_sel:WORD_0
	v_mov_b32_e32 v73, v137
	v_lshl_add_u64 v[74:75], v[152:153], 0, v[136:137]
	v_lshl_add_u64 v[72:73], v[152:153], 0, v[72:73]
	global_load_dwordx4 v[112:115], v[74:75], off
	global_load_dwordx4 v[100:103], v[72:73], off
	s_waitcnt lgkmcnt(0)
	v_lshlrev_b32_sdwa v72, v188, v78 dst_sel:DWORD dst_unused:UNUSED_PAD src0_sel:DWORD src1_sel:WORD_1
	v_lshlrev_b32_sdwa v136, v188, v78 dst_sel:DWORD dst_unused:UNUSED_PAD src0_sel:DWORD src1_sel:WORD_0
	v_mov_b32_e32 v73, v137
	v_lshl_add_u64 v[74:75], v[152:153], 0, v[136:137]
	v_lshl_add_u64 v[72:73], v[152:153], 0, v[72:73]
	global_load_dwordx4 v[104:107], v[74:75], off
	global_load_dwordx4 v[92:95], v[72:73], off
	v_lshlrev_b32_sdwa v72, v188, v79 dst_sel:DWORD dst_unused:UNUSED_PAD src0_sel:DWORD src1_sel:WORD_1
	v_lshlrev_b32_sdwa v136, v188, v79 dst_sel:DWORD dst_unused:UNUSED_PAD src0_sel:DWORD src1_sel:WORD_0
	v_mov_b32_e32 v73, v137
	v_lshl_add_u64 v[74:75], v[152:153], 0, v[136:137]
	v_lshl_add_u64 v[72:73], v[152:153], 0, v[72:73]
	global_load_dwordx4 v[96:99], v[74:75], off
	global_load_dwordx4 v[84:87], v[72:73], off
	v_lshlrev_b32_sdwa v72, v188, v80 dst_sel:DWORD dst_unused:UNUSED_PAD src0_sel:DWORD src1_sel:WORD_1
	v_lshlrev_b32_sdwa v136, v188, v80 dst_sel:DWORD dst_unused:UNUSED_PAD src0_sel:DWORD src1_sel:WORD_0
	v_mov_b32_e32 v73, v137
	v_lshl_add_u64 v[74:75], v[152:153], 0, v[136:137]
	v_lshl_add_u64 v[72:73], v[152:153], 0, v[72:73]
	global_load_dwordx4 v[88:91], v[74:75], off
	global_load_dwordx4 v[76:79], v[72:73], off
	v_lshlrev_b32_sdwa v72, v188, v81 dst_sel:DWORD dst_unused:UNUSED_PAD src0_sel:DWORD src1_sel:WORD_1
	v_lshlrev_b32_sdwa v136, v188, v81 dst_sel:DWORD dst_unused:UNUSED_PAD src0_sel:DWORD src1_sel:WORD_0
	v_mov_b32_e32 v73, v137
	v_lshl_add_u64 v[74:75], v[152:153], 0, v[136:137]
	v_lshl_add_u64 v[72:73], v[152:153], 0, v[72:73]
	global_load_dwordx4 v[80:83], v[74:75], off
	s_nop 0
	global_load_dwordx4 v[72:75], v[72:73], off
	v_lshlrev_b32_e32 v250, 2, v250
	global_load_dword v247, v250, s[40:41]
	global_load_dword v248, v250, s[36:37]
	global_load_dword v249, v250, s[38:39]
	s_mul_i32 s15, s20, s9
	s_mul_i32 s14, s81, s14
	v_mov_b32_e32 v136, v137
	v_mov_b32_e32 v163, v137
	s_waitcnt vmcnt(20)
	v_dot8c_i32_i4_e32 v136, v0, v16
	v_dot8c_i32_i4_e32 v163, v0, v12
	v_dot8c_i32_i4_e32 v136, v1, v17
	v_dot8c_i32_i4_e32 v163, v1, v13
	v_dot8c_i32_i4_e32 v136, v2, v18
	v_dot8c_i32_i4_e32 v163, v2, v14
	v_dot8c_i32_i4_e32 v136, v3, v19
	v_dot8c_i32_i4_e32 v163, v3, v15
	s_add_i32 s15, s16, s15
	s_add_i32 s17, s9, 1
	s_add_i32 s14, s16, s14
	ds_write2st64_b32 v180, v136, v163 offset0:34 offset1:35
	v_mov_b32_e32 v136, v137
	v_mov_b32_e32 v163, v137
	v_dot8c_i32_i4_e32 v136, v0, v8
	v_dot8c_i32_i4_e32 v163, v0, v4
	v_dot8c_i32_i4_e32 v136, v1, v9
	v_dot8c_i32_i4_e32 v163, v1, v5
	v_dot8c_i32_i4_e32 v136, v2, v10
	v_dot8c_i32_i4_e32 v163, v2, v6
	v_dot8c_i32_i4_e32 v136, v3, v11
	v_dot8c_i32_i4_e32 v163, v3, v7
	s_cmp_ge_u32 s15, s81
	s_cselect_b32 s17, s17, s9
	s_cselect_b32 s14, s14, s15
	ds_write2st64_b32 v180, v136, v163 offset0:36 offset1:37
	v_mov_b32_e32 v136, v137
	v_mov_b32_e32 v163, v137
	v_dot8c_i32_i4_e32 v136, v0, v20
	v_dot8c_i32_i4_e32 v163, v0, v24
	v_dot8c_i32_i4_e32 v136, v1, v21
	v_dot8c_i32_i4_e32 v163, v1, v25
	v_dot8c_i32_i4_e32 v136, v2, v22
	v_dot8c_i32_i4_e32 v163, v2, v26
	v_dot8c_i32_i4_e32 v136, v3, v23
	v_dot8c_i32_i4_e32 v163, v3, v27
	s_add_i32 s15, s17, 1
	s_cmp_ge_u32 s14, s81
	s_cselect_b32 s17, s15, s17
	ds_write2st64_b32 v180, v136, v163 offset0:38 offset1:39
	v_mov_b32_e32 v136, v137
	v_mov_b32_e32 v163, v137
	v_dot8c_i32_i4_e32 v136, v0, v28
	v_dot8c_i32_i4_e32 v163, v0, v32
	v_dot8c_i32_i4_e32 v136, v1, v29
	v_dot8c_i32_i4_e32 v163, v1, v33
	v_dot8c_i32_i4_e32 v136, v2, v30
	v_dot8c_i32_i4_e32 v163, v2, v34
	v_dot8c_i32_i4_e32 v136, v3, v31
	v_dot8c_i32_i4_e32 v163, v3, v35
	s_mul_i32 s14, s25, s17
	s_nop 1
	ds_write2st64_b32 v180, v136, v163 offset0:40 offset1:41
	v_mov_b32_e32 v136, v137
	v_mov_b32_e32 v163, v137
	v_dot8c_i32_i4_e32 v136, v0, v36
	v_dot8c_i32_i4_e32 v163, v0, v40
	v_dot8c_i32_i4_e32 v136, v1, v37
	v_dot8c_i32_i4_e32 v163, v1, v41
	v_dot8c_i32_i4_e32 v136, v2, v38
	v_dot8c_i32_i4_e32 v163, v2, v42
	v_dot8c_i32_i4_e32 v136, v3, v39
	v_dot8c_i32_i4_e32 v163, v3, v43
	s_nop 2
	ds_write2st64_b32 v180, v136, v163 offset0:42 offset1:43
	v_mov_b32_e32 v136, v137
	v_mov_b32_e32 v163, v137
	v_dot8c_i32_i4_e32 v136, v0, v44
	v_dot8c_i32_i4_e32 v163, v0, v48
	v_dot8c_i32_i4_e32 v136, v1, v45
	v_dot8c_i32_i4_e32 v163, v1, v49
	v_dot8c_i32_i4_e32 v136, v2, v46
	v_dot8c_i32_i4_e32 v163, v2, v50
	v_dot8c_i32_i4_e32 v136, v3, v47
	v_dot8c_i32_i4_e32 v163, v3, v51
	s_nop 2
	ds_write2st64_b32 v180, v136, v163 offset0:44 offset1:45
	v_mov_b32_e32 v136, v137
	v_mov_b32_e32 v163, v137
	v_dot8c_i32_i4_e32 v136, v0, v52
	v_dot8c_i32_i4_e32 v163, v0, v56
	v_dot8c_i32_i4_e32 v136, v1, v53
	v_dot8c_i32_i4_e32 v163, v1, v57
	v_dot8c_i32_i4_e32 v136, v2, v54
	v_dot8c_i32_i4_e32 v163, v2, v58
	v_dot8c_i32_i4_e32 v136, v3, v55
	v_dot8c_i32_i4_e32 v163, v3, v59
	s_nop 2
	ds_write2st64_b32 v180, v136, v163 offset0:46 offset1:47
	v_mov_b32_e32 v136, v137
	v_mov_b32_e32 v163, v137
	v_dot8c_i32_i4_e32 v136, v0, v60
	v_dot8c_i32_i4_e32 v163, v0, v64
	v_dot8c_i32_i4_e32 v136, v1, v61
	v_dot8c_i32_i4_e32 v163, v1, v65
	v_dot8c_i32_i4_e32 v136, v2, v62
	v_dot8c_i32_i4_e32 v163, v2, v66
	v_dot8c_i32_i4_e32 v136, v3, v63
	v_dot8c_i32_i4_e32 v163, v3, v67
	s_nop 2
	ds_write2st64_b32 v180, v136, v163 offset0:48 offset1:49
	s_waitcnt lgkmcnt(0)
	s_mul_i32 s14, s82, s17
	s_add_i32 s14, s19, s14
	v_add_u32_e32 v169, s14, v176
	ds_read_b128 v[194:197], v189 offset:8704
	ds_read_b128 v[198:201], v189 offset:8720
	ds_read_b128 v[202:205], v189 offset:8736
	ds_read_b128 v[206:209], v189 offset:8752
	s_waitcnt lgkmcnt(3)
	v_add_u32_e32 v167, v195, v194
	v_add3_u32 v167, v167, v196, v197
	s_waitcnt lgkmcnt(2)
	v_add3_u32 v167, v167, v199, v198
	v_add3_u32 v167, v167, v200, v201
	s_waitcnt lgkmcnt(1)
	v_add3_u32 v167, v167, v203, v202
	v_add3_u32 v167, v167, v204, v205
	s_waitcnt lgkmcnt(0)
	v_add3_u32 v167, v167, v207, v206
	v_add3_u32 v167, v167, v208, v209
	ds_read_b64 v[194:195], v169 offset:2304
	s_waitcnt lgkmcnt(0)
	v_mov_b32_e32 v196, v195
	v_add_u32_dpp v167, v167, v167 quad_perm:[1,0,3,2] row_mask:0xf bank_mask:0xf bound_ctrl:1
	v_cvt_f32_i32_e32 v197, v244
	v_add_u32_dpp v167, v167, v167 quad_perm:[2,3,0,1] row_mask:0xf bank_mask:0xf bound_ctrl:1
	v_cvt_f32_i32_e32 v163, v167
	v_pk_mul_f32 v[196:197], v[196:197], 0.5 op_sel_hi:[1,0]
	s_nop 0
	v_add_f32_e32 v163, v197, v163
	v_add_f32_e32 v163, v196, v163
	v_add_f32_e32 v163, 0x44000000, v163
	v_mul_f32_e32 v163, v194, v163
	v_mul_f32_e32 v163, v245, v163
	v_mul_f32_e32 v165, 0x3f3504f3, v163
	v_cmp_nlt_f32_e64 s[14:15], |v165|, 1.0
	s_and_saveexec_b64 s[84:85], s[14:15]
	s_xor_b64 s[14:15], exec, s[84:85]
	s_cbranch_execz .LBB0_792
	v_fma_f32 v167, |v165|, s66, v191
	v_fma_f32 v167, |v165|, v167, s67
	v_fma_f32 v167, |v165|, v167, s68
	v_fma_f32 v167, |v165|, v167, s69
	v_fma_f32 v167, |v165|, v167, s70
	v_fma_f32 v167, |v165|, v167, s71
	v_fma_f32 v167, |v165|, v167, |v165|
	v_mul_f32_e32 v169, 0xbfb8aa3b, v167
	v_fma_f32 v171, v167, s74, -v169
	v_rndne_f32_e32 v173, v169
	v_fmac_f32_e32 v171, 0xb2a5705f, v167
	v_sub_f32_e32 v169, v169, v173
	v_add_f32_e32 v169, v169, v171
	v_cvt_i32_f32_e32 v171, v173
	v_exp_f32_e32 v169, v169
	v_cmp_nlt_f32_e32 vcc, s75, v167
	v_ldexp_f32 v169, v169, v171
	s_nop 0
	v_cndmask_b32_e32 v169, 0, v169, vcc
	v_cmp_ngt_f32_e32 vcc, s76, v167
	s_nop 1
	v_cndmask_b32_e32 v167, v192, v169, vcc
	v_sub_f32_e32 v167, 1.0, v167
.LBB0_792:
	s_andn2_saveexec_b64 s[14:15], s[14:15]
	v_mul_f32_e32 v167, v165, v165
	v_fmamk_f32 v169, v167, 0xba1345e1, v186
	v_fmaak_f32 v169, v167, v169, 0xbcdac9b8
	v_fmaak_f32 v169, v167, v169, 0x3de703be
	v_fmaak_f32 v169, v167, v169, 0xbec09330
	v_fmaak_f32 v167, v167, v169, 0x3e0375d0
	v_fma_f32 v167, |v165|, v167, |v165|
	s_or_b64 exec, exec, s[14:15]
	s_mul_i32 s14, s24, s17
	v_add_u32_e32 v169, s14, v176
	v_add_u32_e32 v169, v159, v169
	ds_read_b32 v171, v169 offset:4608
	s_waitcnt lgkmcnt(0)
	s_and_saveexec_b64 s[14:15], s[4:5]
	s_cbranch_execz .LBB0_796
	v_bfi_b32 v165, s77, v167, v165
	v_mul_f32_e32 v163, 0.5, v163
	v_add_f32_e32 v165, 1.0, v165
	v_mul_f32_e32 v163, v163, v165
	v_mul_f32_e32 v163, v171, v163
	v_mul_f32_e32 v136, v246, v163
	ds_write_b32 v169, v136 offset:4608
.LBB0_796:
	s_or_b64 exec, exec, s[14:15]
	s_add_i32 s84, s16, 2
	s_cmp_ge_i32 s84, s18
	s_cselect_b64 s[14:15], -1, 0
	s_and_b64 vcc, exec, s[14:15]
	s_cbranch_vccnz .Lpeer_skipA
	s_not_b32 s85, s13
	s_mul_i32 s17, s81, s13
	s_mul_i32 s85, s81, s85
	s_add_i32 s85, s85, s16
	s_sub_i32 s17, s16, s17
	s_add_i32 s17, s17, 2
	s_add_i32 s86, s13, 1
	s_add_i32 s85, s85, 2
	s_cmp_ge_u32 s17, s81
	s_cselect_b32 s86, s86, s13
	s_cselect_b32 s17, s85, s17
	s_add_i32 s85, s86, 1
	s_cmp_ge_u32 s17, s81
	s_cselect_b32 s17, s85, s86
	s_mul_i32 s85, s20, s17
	s_add_i32 s16, s16, s85
	s_add_i32 s16, s16, 2
	s_mul_i32 s16, s16, s33
	v_add_u32_e32 v0, s16, v172
	s_mul_i32 s16, s21, s17
	s_add_i32 s16, s26, s16
	v_add_u32_e32 v4, s16, v176
	v_add_u32_e32 v250, v183, v4
	ds_read_b128 v[26:29], v4 offset:3072
	ds_read_b128 v[58:61], v4 offset:3088
	ds_read_u16 v250, v250 offset:3072
	v_ashrrev_i32_e32 v1, 31, v0
	v_lshlrev_b64 v[0:1], 10, v[0:1]
	v_lshl_add_u64 v[0:1], v[138:139], 0, v[0:1]
	s_waitcnt lgkmcnt(1)
	v_lshlrev_b32_sdwa v136, v188, v26 dst_sel:DWORD dst_unused:UNUSED_PAD src0_sel:DWORD src1_sel:WORD_0
	v_lshlrev_b32_sdwa v4, v188, v26 dst_sel:DWORD dst_unused:UNUSED_PAD src0_sel:DWORD src1_sel:WORD_1
	v_lshl_add_u64 v[6:7], v[152:153], 0, v[136:137]
	v_mov_b32_e32 v5, v137
	v_lshlrev_b32_sdwa v136, v188, v27 dst_sel:DWORD dst_unused:UNUSED_PAD src0_sel:DWORD src1_sel:WORD_0
	global_load_dwordx4 v[0:3], v[0:1], off
	v_lshl_add_u64 v[4:5], v[152:153], 0, v[4:5]
	global_load_dwordx4 v[16:19], v[6:7], off
	global_load_dwordx4 v[12:15], v[4:5], off
	v_lshl_add_u64 v[6:7], v[152:153], 0, v[136:137]
	v_lshlrev_b32_sdwa v136, v188, v28 dst_sel:DWORD dst_unused:UNUSED_PAD src0_sel:DWORD src1_sel:WORD_0
	v_lshl_add_u64 v[22:23], v[152:153], 0, v[136:137]
	v_lshlrev_b32_sdwa v136, v188, v29 dst_sel:DWORD dst_unused:UNUSED_PAD src0_sel:DWORD src1_sel:WORD_0
	v_lshl_add_u64 v[30:31], v[152:153], 0, v[136:137]
	s_waitcnt lgkmcnt(0)
	v_lshlrev_b32_sdwa v136, v188, v58 dst_sel:DWORD dst_unused:UNUSED_PAD src0_sel:DWORD src1_sel:WORD_0
	v_lshl_add_u64 v[38:39], v[152:153], 0, v[136:137]
	v_lshlrev_b32_sdwa v136, v188, v59 dst_sel:DWORD dst_unused:UNUSED_PAD src0_sel:DWORD src1_sel:WORD_0
	v_lshl_add_u64 v[46:47], v[152:153], 0, v[136:137]
	v_lshlrev_b32_sdwa v136, v188, v60 dst_sel:DWORD dst_unused:UNUSED_PAD src0_sel:DWORD src1_sel:WORD_0
	v_lshlrev_b32_sdwa v4, v188, v27 dst_sel:DWORD dst_unused:UNUSED_PAD src0_sel:DWORD src1_sel:WORD_1
	v_mov_b32_e32 v5, v137
	v_lshlrev_b32_sdwa v20, v188, v28 dst_sel:DWORD dst_unused:UNUSED_PAD src0_sel:DWORD src1_sel:WORD_1
	v_mov_b32_e32 v21, v137
	v_lshlrev_b32_sdwa v28, v188, v29 dst_sel:DWORD dst_unused:UNUSED_PAD src0_sel:DWORD src1_sel:WORD_1
	v_mov_b32_e32 v29, v137
	v_lshlrev_b32_sdwa v36, v188, v58 dst_sel:DWORD dst_unused:UNUSED_PAD src0_sel:DWORD src1_sel:WORD_1
	v_mov_b32_e32 v37, v137
	v_lshlrev_b32_sdwa v44, v188, v59 dst_sel:DWORD dst_unused:UNUSED_PAD src0_sel:DWORD src1_sel:WORD_1
	v_mov_b32_e32 v45, v137
	v_lshlrev_b32_sdwa v52, v188, v60 dst_sel:DWORD dst_unused:UNUSED_PAD src0_sel:DWORD src1_sel:WORD_1
	v_lshl_add_u64 v[54:55], v[152:153], 0, v[136:137]
	v_mov_b32_e32 v53, v137
	v_lshlrev_b32_sdwa v60, v188, v61 dst_sel:DWORD dst_unused:UNUSED_PAD src0_sel:DWORD src1_sel:WORD_1
	v_lshlrev_b32_sdwa v136, v188, v61 dst_sel:DWORD dst_unused:UNUSED_PAD src0_sel:DWORD src1_sel:WORD_0
	v_mov_b32_e32 v61, v137
	v_lshl_add_u64 v[4:5], v[152:153], 0, v[4:5]
	v_lshl_add_u64 v[24:25], v[152:153], 0, v[20:21]
	v_lshl_add_u64 v[32:33], v[152:153], 0, v[28:29]
	v_lshl_add_u64 v[40:41], v[152:153], 0, v[36:37]
	v_lshl_add_u64 v[48:49], v[152:153], 0, v[44:45]
	v_lshl_add_u64 v[56:57], v[152:153], 0, v[52:53]
	v_lshl_add_u64 v[62:63], v[152:153], 0, v[136:137]
	v_lshl_add_u64 v[64:65], v[152:153], 0, v[60:61]
	global_load_dwordx4 v[8:11], v[6:7], off
	s_nop 0
	global_load_dwordx4 v[4:7], v[4:5], off
	s_nop 0
	global_load_dwordx4 v[20:23], v[22:23], off
	s_nop 0
	global_load_dwordx4 v[24:27], v[24:25], off
	s_nop 0
	global_load_dwordx4 v[28:31], v[30:31], off
	s_nop 0
	global_load_dwordx4 v[32:35], v[32:33], off
	s_nop 0
	global_load_dwordx4 v[36:39], v[38:39], off
	s_nop 0
	global_load_dwordx4 v[40:43], v[40:41], off
	s_nop 0
	global_load_dwordx4 v[44:47], v[46:47], off
	s_nop 0
	global_load_dwordx4 v[48:51], v[48:49], off
	s_nop 0
	global_load_dwordx4 v[52:55], v[54:55], off
	s_nop 0
	global_load_dwordx4 v[56:59], v[56:57], off
	s_nop 0
	global_load_dwordx4 v[60:63], v[62:63], off
	s_nop 0
	global_load_dwordx4 v[64:67], v[64:65], off
	v_lshlrev_b32_e32 v250, 2, v250
	global_load_dword v244, v250, s[40:41]
	global_load_dword v245, v250, s[36:37]
	global_load_dword v246, v250, s[38:39]
	s_waitcnt vmcnt(20)
	s_branch .LBB0_798

.LBB0_798:
	v_mov_b32_e32 v136, v137
	v_dot8c_i32_i4_e32 v136, v68, v132
	v_mov_b32_e32 v132, v137
	v_dot8c_i32_i4_e32 v132, v68, v124
	v_dot8c_i32_i4_e32 v132, v69, v125
	v_mov_b32_e32 v125, v137
	v_dot8c_i32_i4_e32 v125, v68, v116
	v_dot8c_i32_i4_e32 v125, v69, v117
	v_mov_b32_e32 v117, v137
	v_dot8c_i32_i4_e32 v117, v68, v108
	v_dot8c_i32_i4_e32 v117, v69, v109
	v_mov_b32_e32 v109, v137
	v_dot8c_i32_i4_e32 v109, v68, v100
	v_dot8c_i32_i4_e32 v109, v69, v101
	v_mov_b32_e32 v101, v137
	v_dot8c_i32_i4_e32 v101, v68, v92
	v_dot8c_i32_i4_e32 v101, v69, v93
	v_mov_b32_e32 v93, v137
	v_dot8c_i32_i4_e32 v93, v68, v84
	v_dot8c_i32_i4_e32 v93, v69, v85
	v_mov_b32_e32 v85, v137
	v_dot8c_i32_i4_e32 v85, v68, v76
	v_mov_b32_e32 v124, v137
	v_mov_b32_e32 v116, v137
	v_mov_b32_e32 v108, v137
	v_mov_b32_e32 v100, v137
	v_mov_b32_e32 v92, v137
	v_mov_b32_e32 v84, v137
	v_dot8c_i32_i4_e32 v85, v69, v77
	v_mov_b32_e32 v76, v137
	v_mov_b32_e32 v77, v137
	v_dot8c_i32_i4_e32 v124, v68, v128
	v_dot8c_i32_i4_e32 v116, v68, v120
	v_dot8c_i32_i4_e32 v108, v68, v112
	v_dot8c_i32_i4_e32 v100, v68, v104
	v_dot8c_i32_i4_e32 v92, v68, v96
	v_dot8c_i32_i4_e32 v84, v68, v88
	v_dot8c_i32_i4_e32 v76, v68, v80
	v_dot8c_i32_i4_e32 v77, v68, v72
	v_dot8c_i32_i4_e32 v136, v69, v133
	v_dot8c_i32_i4_e32 v124, v69, v129
	v_dot8c_i32_i4_e32 v116, v69, v121
	v_dot8c_i32_i4_e32 v108, v69, v113
	v_dot8c_i32_i4_e32 v100, v69, v105
	v_dot8c_i32_i4_e32 v92, v69, v97
	v_dot8c_i32_i4_e32 v84, v69, v89
	v_dot8c_i32_i4_e32 v76, v69, v81
	v_dot8c_i32_i4_e32 v77, v69, v73
	v_dot8c_i32_i4_e32 v136, v70, v134
	v_dot8c_i32_i4_e32 v132, v70, v126
	v_dot8c_i32_i4_e32 v124, v70, v130
	v_dot8c_i32_i4_e32 v125, v70, v118
	v_dot8c_i32_i4_e32 v116, v70, v122
	v_dot8c_i32_i4_e32 v117, v70, v110
	v_dot8c_i32_i4_e32 v108, v70, v114
	v_dot8c_i32_i4_e32 v109, v70, v102
	v_dot8c_i32_i4_e32 v100, v70, v106
	v_dot8c_i32_i4_e32 v101, v70, v94
	v_dot8c_i32_i4_e32 v92, v70, v98
	v_dot8c_i32_i4_e32 v93, v70, v86
	v_dot8c_i32_i4_e32 v84, v70, v90
	v_dot8c_i32_i4_e32 v85, v70, v78
	v_dot8c_i32_i4_e32 v76, v70, v82
	v_dot8c_i32_i4_e32 v77, v70, v74
	v_dot8c_i32_i4_e32 v136, v71, v135
	v_dot8c_i32_i4_e32 v132, v71, v127
	v_dot8c_i32_i4_e32 v124, v71, v131
	v_dot8c_i32_i4_e32 v125, v71, v119
	v_dot8c_i32_i4_e32 v116, v71, v123
	v_dot8c_i32_i4_e32 v117, v71, v111
	v_dot8c_i32_i4_e32 v108, v71, v115
	v_dot8c_i32_i4_e32 v109, v71, v103
	v_dot8c_i32_i4_e32 v100, v71, v107
	v_dot8c_i32_i4_e32 v101, v71, v95
	v_dot8c_i32_i4_e32 v92, v71, v99
	v_dot8c_i32_i4_e32 v93, v71, v87
	v_dot8c_i32_i4_e32 v84, v71, v91
	v_dot8c_i32_i4_e32 v85, v71, v79
	v_dot8c_i32_i4_e32 v76, v71, v83
	v_dot8c_i32_i4_e32 v77, v71, v75
	v_add_u32_e32 v68, v157, v161
	ds_write2st64_b32 v180, v136, v132 offset0:34 offset1:35
	ds_write2st64_b32 v180, v124, v125 offset0:36 offset1:37
	ds_write2st64_b32 v180, v116, v117 offset0:38 offset1:39
	ds_write2st64_b32 v180, v108, v109 offset0:40 offset1:41
	ds_write2st64_b32 v180, v100, v101 offset0:42 offset1:43
	ds_write2st64_b32 v180, v92, v93 offset0:44 offset1:45
	ds_write2st64_b32 v180, v84, v85 offset0:46 offset1:47
	ds_write2st64_b32 v180, v76, v77 offset0:48 offset1:49
	s_waitcnt lgkmcnt(0)
	s_mul_i32 s16, s82, s83
	s_add_i32 s16, s19, s16
	ds_read_b128 v[70:73], v189 offset:8704
	ds_read_b128 v[74:77], v189 offset:8720
	ds_read_b128 v[78:81], v189 offset:8736
	ds_read_b128 v[82:85], v189 offset:8752
	s_waitcnt lgkmcnt(3)
	v_add_u32_e32 v70, v71, v70
	v_add3_u32 v70, v70, v72, v73
	s_waitcnt lgkmcnt(2)
	v_add3_u32 v70, v70, v75, v74
	v_add3_u32 v70, v70, v76, v77
	s_waitcnt lgkmcnt(1)
	v_add3_u32 v70, v70, v79, v78
	v_add3_u32 v70, v70, v80, v81
	s_waitcnt lgkmcnt(0)
	v_add3_u32 v70, v70, v83, v82
	v_add3_u32 v70, v70, v84, v85
	v_cvt_f32_i32_e32 v73, v247
	v_add_u32_dpp v72, v70, v70 quad_perm:[1,0,3,2] row_mask:0xf bank_mask:0xf bound_ctrl:1
	v_add_u32_e32 v70, s16, v176
	ds_read_b64 v[70:71], v70 offset:2312
	v_add_u32_dpp v72, v72, v72 quad_perm:[2,3,0,1] row_mask:0xf bank_mask:0xf bound_ctrl:1
	v_cvt_f32_i32_e32 v69, v72
	s_waitcnt lgkmcnt(0)
	v_mov_b32_e32 v72, v71
	v_pk_mul_f32 v[72:73], v[72:73], 0.5 op_sel_hi:[1,0]
	s_nop 0
	v_add_f32_e32 v69, v73, v69
	v_add_f32_e32 v69, v72, v69
	v_add_f32_e32 v69, 0x44000000, v69
	v_mul_f32_e32 v69, v70, v69
	v_mul_f32_e32 v69, v248, v69
	v_mul_f32_e32 v70, 0x3f3504f3, v69
	v_cmp_nlt_f32_e64 s[16:17], |v70|, 1.0
	s_and_saveexec_b64 s[86:87], s[16:17]
	s_xor_b64 s[16:17], exec, s[86:87]
	s_cbranch_execz .LBB0_800
	v_fma_f32 v71, |v70|, s66, v191
	v_fma_f32 v71, |v70|, v71, s67
	v_fma_f32 v71, |v70|, v71, s68
	v_fma_f32 v71, |v70|, v71, s69
	v_fma_f32 v71, |v70|, v71, s70
	v_fma_f32 v71, |v70|, v71, s71
	v_fma_f32 v71, |v70|, v71, |v70|
	v_mul_f32_e32 v72, 0xbfb8aa3b, v71
	v_fma_f32 v73, v71, s74, -v72
	v_rndne_f32_e32 v74, v72
	v_fmac_f32_e32 v73, 0xb2a5705f, v71
	v_sub_f32_e32 v72, v72, v74
	v_add_f32_e32 v72, v72, v73
	v_cvt_i32_f32_e32 v73, v74
	v_exp_f32_e32 v72, v72
	v_cmp_nlt_f32_e32 vcc, s75, v71
	v_ldexp_f32 v72, v72, v73
	s_nop 0
	v_cndmask_b32_e32 v72, 0, v72, vcc
	v_cmp_ngt_f32_e32 vcc, s76, v71
	s_nop 1
	v_cndmask_b32_e32 v71, v192, v72, vcc
	v_sub_f32_e32 v71, 1.0, v71
.LBB0_800:
	s_andn2_saveexec_b64 s[16:17], s[16:17]
	v_mul_f32_e32 v71, v70, v70
	v_fmamk_f32 v72, v71, 0xba1345e1, v186
	v_fmaak_f32 v72, v71, v72, 0xbcdac9b8
	v_fmaak_f32 v72, v71, v72, 0x3de703be
	v_fmaak_f32 v72, v71, v72, 0xbec09330
	v_fmaak_f32 v71, v71, v72, 0x3e0375d0
	v_fma_f32 v71, |v70|, v71, |v70|
	s_or_b64 exec, exec, s[16:17]
	s_mul_i32 s16, s24, s83
	v_add_u32_e32 v72, s16, v176
	v_add_u32_e32 v72, v159, v72
	ds_read_b32 v73, v72 offset:5120
	s_waitcnt lgkmcnt(0)
	s_and_saveexec_b64 s[16:17], s[4:5]
	s_cbranch_execz .LBB0_789
	v_bfi_b32 v70, s77, v71, v70
	v_mul_f32_e32 v69, 0.5, v69
	v_add_f32_e32 v70, 1.0, v70
	v_mul_f32_e32 v69, v69, v70
	v_mul_f32_e32 v69, v73, v69
	v_mul_f32_e32 v68, v249, v69
	ds_write_b32 v72, v68 offset:5120
	s_branch .LBB0_789
